# speedup vs baseline: 1.0081x; 1.0017x over previous
; __device__ __forceinline__ void qkt(f32x16& p0, f32x16& p1, const char* Ks, const bf16x8* qr, int r32, int hi) {
;     p0 = f32x16{}; p1 = f32x16{};
; #pragma unroll
;     for (int d0 = 0; d0 < 8; ++d0) { const int cb = (d0 * 16 + hi * 8) * 2;
;         bf16x8 b0 = *reinterpret_cast<const bf16x8*>(Ks + KSWZ(r32, cb));
;         bf16x8 b1 = *reinterpret_cast<const bf16x8*>(Ks + KSWZ(32 + r32, cb));
;         p0 = __builtin_amdgcn_mfma_f32_32x32x16_bf16(b0, qr[d0], p0, 0, 0, 0);
;         p1 = __builtin_amdgcn_mfma_f32_32x32x16_bf16(b1, qr[d0], p1, 0, 0, 0); }
; }
; template <int LDQ, int LDK, int LDV, int LDO>
; __device__ __forceinline__ void attn256_body(const int tid, const bf16_t* __restrict__ Qb, const bf16_t* __restrict__ Kh, const bf16_t* __restrict__ Vh, bf16_t* __restrict__ Ob, int seq, char* lds, LAS unsigned char* ldsl) {
;     ...
;     for (int j = 0; j < NT; ++j) {
;         const int b = j & 1;
;         asm volatile("s_waitcnt vmcnt(0)" ::: "memory"); __builtin_amdgcn_s_barrier(); asm volatile("" ::: "memory");
;         if (j + 1 < NT) A2_ISSUE(j + 1, b ^ 1);
;         f32x16 p0, p1;
;         qkt(p0, p1, lds + A2_KOFF + b * 16384, qr, r32, hi);
.LBB0_134:
	s_waitcnt lgkmcnt(2)
	v_mfma_f32_32x32x16_bf16 v[130:145], v[224:227], v[162:165], 0
	ds_read_b128 v[224:227], v219
	s_add_i32 m0, s21, 0x4000
	s_nop 0
	global_load_lds_dwordx4 v206, s[6:7]
	v_mfma_f32_32x32x16_bf16 v[130:145], v[228:231], v[166:169], v[130:145]
	ds_read_b128 v[228:231], v220
	s_add_i32 m0, s21, 0x6000
	s_nop 0
	global_load_lds_dwordx4 v204, s[6:7]
	v_mfma_f32_32x32x16_bf16 v[130:145], v[232:235], v[170:173], v[130:145]
	ds_read_b128 v[232:235], v212 offset:8192
	s_add_i32 m0, s21, 0x10000
	s_nop 0
	global_load_lds_dwordx4 v196, s[36:37]
	v_mfma_f32_32x32x16_bf16 v[130:145], v[236:239], v[174:177], v[130:145]
	ds_read_b128 v[236:239], v213 offset:8192
	s_add_i32 m0, s21, 0x12000
	s_nop 0
	global_load_lds_dwordx4 v198, s[36:37]
	s_waitcnt lgkmcnt(2)
	v_mfma_f32_32x32x16_bf16 v[130:145], v[244:247], v[178:181], v[130:145]
	ds_read_b128 v[244:247], v214 offset:8192
	s_add_i32 m0, s21, 0x14000
	s_nop 0
	global_load_lds_dwordx4 v200, s[36:37]
	v_mfma_f32_32x32x16_bf16 v[130:145], v[248:251], v[182:185], v[130:145]
	ds_read_b128 v[248:251], v215 offset:8192
	s_add_i32 m0, s21, 0x16000
	s_nop 0
	global_load_lds_dwordx4 v202, s[36:37]
	v_mfma_f32_32x32x16_bf16 v[130:145], v[224:227], v[186:189], v[130:145]
	ds_read_b128 v[224:227], v216 offset:8192
	v_mfma_f32_32x32x16_bf16 v[130:145], v[228:231], v[190:193], v[130:145]
	ds_read_b128 v[228:231], v218 offset:8192
	s_waitcnt lgkmcnt(2)
	v_mfma_f32_32x32x16_bf16 v[146:161], v[232:235], v[162:165], 0
	ds_read_b128 v[232:235], v219 offset:8192
	v_mfma_f32_32x32x16_bf16 v[146:161], v[236:239], v[166:169], v[146:161]
	ds_read_b128 v[236:239], v220 offset:8192
	v_mfma_f32_32x32x16_bf16 v[146:161], v[244:247], v[170:173], v[146:161]
	ds_read_b64_tr_b16 v[244:245], v221 offset:0x0
	ds_read_b64_tr_b16 v[246:247], v221 offset:0x800
	v_mfma_f32_32x32x16_bf16 v[146:161], v[248:251], v[174:177], v[146:161]
	ds_read_b64_tr_b16 v[248:249], v221 offset:0x200
	ds_read_b64_tr_b16 v[250:251], v221 offset:0xa00
	v_max3_f32 v0, v130, v131, v132
	v_max3_f32 v0, v0, v133, v134
	s_waitcnt lgkmcnt(4)
	v_mfma_f32_32x32x16_bf16 v[146:161], v[224:227], v[178:181], v[146:161]
	ds_read_b64_tr_b16 v[224:225], v221 offset:0x400
	ds_read_b64_tr_b16 v[226:227], v221 offset:0xc00
	v_max3_f32 v0, v0, v135, v136
	v_max3_f32 v0, v0, v137, v138
	v_mfma_f32_32x32x16_bf16 v[146:161], v[228:231], v[182:185], v[146:161]
	ds_read_b64_tr_b16 v[228:229], v221 offset:0x600
	ds_read_b64_tr_b16 v[230:231], v221 offset:0xe00
	v_max3_f32 v0, v0, v139, v140
	v_max3_f32 v0, v0, v141, v142
	v_mfma_f32_32x32x16_bf16 v[146:161], v[232:235], v[186:189], v[146:161]
	ds_read_b64_tr_b16 v[232:233], v221 offset:0x4000
	ds_read_b64_tr_b16 v[234:235], v221 offset:0x4800
	v_max3_f32 v0, v0, v143, v144
	v_max_f32_e32 v0, v0, v145
	v_mfma_f32_32x32x16_bf16 v[146:161], v[236:239], v[190:193], v[146:161]
	ds_read_b64_tr_b16 v[236:237], v221 offset:0x4200
	ds_read_b64_tr_b16 v[238:239], v221 offset:0x4a00
	s_add_u32 s6, s6, 0x40000
	s_addc_u32 s7, s7, 0
	s_add_u32 s36, s36, 0xe0000
	s_addc_u32 s37, s37, 0
	s_add_i32 s23, s23, 1
	s_nop 4
	v_max3_f32 v0, v0, v146, v147
	v_max3_f32 v0, v0, v148, v149
	v_max3_f32 v0, v0, v150, v151
	v_max3_f32 v0, v0, v152, v153
	v_max3_f32 v0, v0, v154, v155
	v_max3_f32 v0, v0, v156, v157
	v_max3_f32 v0, v0, v158, v159
	v_max3_f32 v0, v0, v160, v161
	v_mov_b32_e32 v240, v0
	s_nop 1
	v_permlane32_swap_b32_e32 v0, v240
	v_max_f32_e32 v0, v0, v240
	v_sub_f32_e32 v240, v0, v222
	v_cmp_ge_f32_e32 vcc, 0x42b504f3, v240
	s_cmp_eq_u64 vcc, exec
	v_max_f32_e32 v0, v222, v0
	s_cselect_b64 vcc, -1, 0
	v_sub_f32_e32 v240, v222, v0
	v_cndmask_b32_e32 v222, v0, v222, vcc
	v_mul_f32_e32 v240, 0x3e0293ee, v240
	v_mul_f32_e32 v0, 0xbe0293ee, v222
	v_exp_f32_e32 v243, v240
	v_fmamk_f32 v130, v130, 0x3e0293ee, v0
	v_fmamk_f32 v131, v131, 0x3e0293ee, v0
	v_fmamk_f32 v132, v132, 0x3e0293ee, v0
	v_fmamk_f32 v133, v133, 0x3e0293ee, v0
	v_fmamk_f32 v134, v134, 0x3e0293ee, v0
	v_fmamk_f32 v135, v135, 0x3e0293ee, v0
	v_fmamk_f32 v136, v136, 0x3e0293ee, v0
	v_fmamk_f32 v137, v137, 0x3e0293ee, v0
	v_cndmask_b32_e64 v243, v243, 1.0, vcc
	v_cmp_gt_f32_e32 vcc, 1.0, v243
	s_cbranch_vccnz .Lattn_rescale_b0

; __device__ __forceinline__ void qkt(f32x16& p0, f32x16& p1, const char* Ks, const bf16x8* qr, int r32, int hi) {
;     ...
;     for (int d0 = 0; d0 < 8; ++d0) { const int cb = (d0 * 16 + hi * 8) * 2;
;         bf16x8 b0 = *reinterpret_cast<const bf16x8*>(Ks + KSWZ(r32, cb));
;         bf16x8 b1 = *reinterpret_cast<const bf16x8*>(Ks + KSWZ(32 + r32, cb));
;         p0 = __builtin_amdgcn_mfma_f32_32x32x16_bf16(b0, qr[d0], p0, 0, 0, 0);
;         p1 = __builtin_amdgcn_mfma_f32_32x32x16_bf16(b1, qr[d0], p1, 0, 0, 0); }
; template <int LDQ, int LDK, int LDV, int LDO>
; __device__ __forceinline__ void attn256_body(const int tid, const bf16_t* __restrict__ Qb, const bf16_t* __restrict__ Kh, const bf16_t* __restrict__ Vh, bf16_t* __restrict__ Ob, int seq, char* lds, LAS unsigned char* ldsl) {
;     ...
;         if (j + 1 < NT) A2_ISSUE(j + 1, b ^ 1);
;         f32x16 p0, p1;
;         qkt(p0, p1, lds + A2_KOFF + b * 16384, qr, r32, hi);
;         float pmax = p0[0];
; #pragma unroll
;         for (int r = 1; r < 16; ++r) pmax = fmaxf(pmax, p0[r]);
; #pragma unroll
;         for (int r = 0; r < 16; ++r) pmax = fmaxf(pmax, p1[r]);
;         { auto rr = __builtin_amdgcn_permlane32_swap(__float_as_uint(pmax), __float_as_uint(pmax), false, false); pmax = fmaxf(__uint_as_float(rr[0]), __uint_as_float(rr[1])); }
;         float alpha = 1.f;
;         if (!__all(pmax - m_reg <= ATT_THR / ATT_SCALE)) { const float mn = fmaxf(m_reg, pmax); alpha = __builtin_amdgcn_exp2f((m_reg - mn) * C); m_reg = mn; }
;         const float mnC = -m_reg * C;
.Lattn_top_b1:
	s_waitcnt lgkmcnt(2)
	v_mfma_f32_32x32x16_bf16 v[130:145], v[224:227], v[162:165], 0
	ds_read_b128 v[224:227], v219 offset:16384
	s_cmp_eq_u32 s23, 63
	s_cbranch_scc1 .Lattn_nd0_b1
	s_mov_b32 m0, s21
	s_nop 0
	global_load_lds_dwordx4 v206, s[6:7]
.Lattn_nd0_b1:
	v_mfma_f32_32x32x16_bf16 v[130:145], v[228:231], v[166:169], v[130:145]
	ds_read_b128 v[228:231], v220 offset:16384
	s_cmp_eq_u32 s23, 63
	s_cbranch_scc1 .Lattn_nd1_b1
	s_add_i32 m0, s21, 0x2000
	s_nop 0
	global_load_lds_dwordx4 v204, s[6:7]
.Lattn_nd1_b1:
	v_mfma_f32_32x32x16_bf16 v[130:145], v[232:235], v[170:173], v[130:145]
	ds_read_b128 v[232:235], v212 offset:24576
	s_cmp_eq_u32 s23, 63
	s_cbranch_scc1 .Lattn_nd2_b1
	s_add_i32 m0, s21, 0x8000
	s_nop 0
	global_load_lds_dwordx4 v196, s[36:37]
.Lattn_nd2_b1:
	v_mfma_f32_32x32x16_bf16 v[130:145], v[236:239], v[174:177], v[130:145]
	ds_read_b128 v[236:239], v213 offset:24576
	s_cmp_eq_u32 s23, 63
	s_cbranch_scc1 .Lattn_nd3_b1
	s_add_i32 m0, s21, 0xa000
	s_nop 0
	global_load_lds_dwordx4 v198, s[36:37]
.Lattn_nd3_b1:
	s_waitcnt lgkmcnt(2)
	v_mfma_f32_32x32x16_bf16 v[130:145], v[244:247], v[178:181], v[130:145]
	ds_read_b128 v[244:247], v214 offset:24576
	s_cmp_eq_u32 s23, 63
	s_cbranch_scc1 .Lattn_nd4_b1
	s_add_i32 m0, s21, 0xc000
	s_nop 0
	global_load_lds_dwordx4 v200, s[36:37]
.Lattn_nd4_b1:
	v_mfma_f32_32x32x16_bf16 v[130:145], v[248:251], v[182:185], v[130:145]
	ds_read_b128 v[248:251], v215 offset:24576
	s_cmp_eq_u32 s23, 63
	s_cbranch_scc1 .Lattn_nd5_b1
	s_add_i32 m0, s21, 0xe000
	s_nop 0
	global_load_lds_dwordx4 v202, s[36:37]
.Lattn_nd5_b1:
	v_mfma_f32_32x32x16_bf16 v[130:145], v[224:227], v[186:189], v[130:145]
	ds_read_b128 v[224:227], v216 offset:24576
	v_mfma_f32_32x32x16_bf16 v[130:145], v[228:231], v[190:193], v[130:145]
	ds_read_b128 v[228:231], v218 offset:24576
	s_waitcnt lgkmcnt(2)
	v_mfma_f32_32x32x16_bf16 v[146:161], v[232:235], v[162:165], 0
	ds_read_b128 v[232:235], v219 offset:24576
	v_mfma_f32_32x32x16_bf16 v[146:161], v[236:239], v[166:169], v[146:161]
	ds_read_b128 v[236:239], v220 offset:24576
	v_mfma_f32_32x32x16_bf16 v[146:161], v[244:247], v[170:173], v[146:161]
	ds_read_b64_tr_b16 v[244:245], v221 offset:0x8000
	ds_read_b64_tr_b16 v[246:247], v221 offset:0x8800
	v_mfma_f32_32x32x16_bf16 v[146:161], v[248:251], v[174:177], v[146:161]
	ds_read_b64_tr_b16 v[248:249], v221 offset:0x8200
	ds_read_b64_tr_b16 v[250:251], v221 offset:0x8a00
	v_max3_f32 v0, v130, v131, v132
	v_max3_f32 v0, v0, v133, v134
	s_waitcnt lgkmcnt(4)
	v_mfma_f32_32x32x16_bf16 v[146:161], v[224:227], v[178:181], v[146:161]
	ds_read_b64_tr_b16 v[224:225], v221 offset:0x8400
	ds_read_b64_tr_b16 v[226:227], v221 offset:0x8c00
	v_max3_f32 v0, v0, v135, v136
	v_max3_f32 v0, v0, v137, v138
	v_mfma_f32_32x32x16_bf16 v[146:161], v[228:231], v[182:185], v[146:161]
	ds_read_b64_tr_b16 v[228:229], v221 offset:0x8600
	ds_read_b64_tr_b16 v[230:231], v221 offset:0x8e00
	v_max3_f32 v0, v0, v139, v140
	v_max3_f32 v0, v0, v141, v142
	v_mfma_f32_32x32x16_bf16 v[146:161], v[232:235], v[186:189], v[146:161]
	ds_read_b64_tr_b16 v[232:233], v221 offset:0xc000
	ds_read_b64_tr_b16 v[234:235], v221 offset:0xc800
	v_max3_f32 v0, v0, v143, v144
	v_max_f32_e32 v0, v0, v145
	v_mfma_f32_32x32x16_bf16 v[146:161], v[236:239], v[190:193], v[146:161]
	ds_read_b64_tr_b16 v[236:237], v221 offset:0xc200
	ds_read_b64_tr_b16 v[238:239], v221 offset:0xca00
	s_add_u32 s6, s6, 0x40000
	s_addc_u32 s7, s7, 0
	s_add_u32 s36, s36, 0xe0000
	s_addc_u32 s37, s37, 0
	s_add_i32 s23, s23, 1
	s_nop 4
	v_max3_f32 v0, v0, v146, v147
	v_max3_f32 v0, v0, v148, v149
	v_max3_f32 v0, v0, v150, v151
	v_max3_f32 v0, v0, v152, v153
	v_max3_f32 v0, v0, v154, v155
	v_max3_f32 v0, v0, v156, v157
	v_max3_f32 v0, v0, v158, v159
	v_max3_f32 v0, v0, v160, v161
	v_mov_b32_e32 v240, v0
	s_nop 1
	v_permlane32_swap_b32_e32 v0, v240
	v_max_f32_e32 v0, v0, v240
	v_sub_f32_e32 v240, v0, v222
	v_cmp_ge_f32_e32 vcc, 0x42b504f3, v240
	s_cmp_eq_u64 vcc, exec
	v_max_f32_e32 v0, v222, v0
	s_cselect_b64 vcc, -1, 0
	v_sub_f32_e32 v240, v222, v0
	v_cndmask_b32_e32 v222, v0, v222, vcc
	v_mul_f32_e32 v240, 0x3e0293ee, v240
	v_mul_f32_e32 v0, 0xbe0293ee, v222
	v_exp_f32_e32 v243, v240
	v_fmamk_f32 v130, v130, 0x3e0293ee, v0
	v_fmamk_f32 v131, v131, 0x3e0293ee, v0
	v_fmamk_f32 v132, v132, 0x3e0293ee, v0
	v_fmamk_f32 v133, v133, 0x3e0293ee, v0
	v_fmamk_f32 v134, v134, 0x3e0293ee, v0
	v_fmamk_f32 v135, v135, 0x3e0293ee, v0
	v_fmamk_f32 v136, v136, 0x3e0293ee, v0
	v_fmamk_f32 v137, v137, 0x3e0293ee, v0
	v_cndmask_b32_e64 v243, v243, 1.0, vcc
	v_cmp_gt_f32_e32 vcc, 1.0, v243
	s_cbranch_vccnz .Lattn_rescale_b1
